# w_up conversion moved to barrier 2's shadow on workgroups 192..255 (gain loads issued together), w_dn in barrier 4's shadow, grid barriers 6/7 XCD-local when the census shows one blockIdx%8 class per
# baseline (speedup 1.0000x reference)
; #define LAS __attribute__((address_space(3)))
; __device__ __forceinline__ unsigned xb_add(unsigned* p, unsigned v) { return __hip_atomic_fetch_add(p, v, __ATOMIC_RELAXED, __HIP_MEMORY_SCOPE_AGENT); }
; __device__ __forceinline__ unsigned xb_xcc_id() { return (unsigned)__builtin_amdgcn_s_getreg((3 << 11) | 20) & 0xFu; }
; __device__ __forceinline__ XcdBarrier xcd_barrier_post(unsigned* bar, volatile LAS unsigned* st) {
;     XcdBarrier b; b.bar = bar; b.x = xb_xcc_id(); b.st = st;
;     if (threadIdx.x == 0) (void)xb_add(&bar[XB_XCNT(b.x)], 1u);
;     return b;
; }
; __global__ void __launch_bounds__(NTHREADS, 2) fwd_megakernel(Args a) {
;     ...
;     if (threadIdx.x < 16) MISC[threadIdx.x] = 0u;
;     __syncthreads();
;     XcdBarrier bar = xcd_barrier_post((unsigned*)(ws + WS_BAR), MISC + 8);
_Z14fwd_megakernel4Args:
	s_load_dwordx4 s[92:95], s[0:1], 0xc0
	s_load_dword s34, s[0:1], 0xd0
	s_add_u32 s6, s0, 0xc8
	v_and_b32_e32 v210, 0x3ff, v0
	s_addc_u32 s7, s1, 0
	v_mov_b32_e32 v1, v210
	v_cmp_gt_u32_e32 vcc, 16, v210
	v_lshl_add_u32 v170, v210, 2, 0
	s_and_saveexec_b64 s[4:5], vcc
	v_add_u32_e32 v1, 0x23000, v170
	v_mov_b32_e32 v2, 0
	ds_write_b32 v1, v2
	s_or_b64 exec, exec, s[4:5]
	s_waitcnt lgkmcnt(0)
	s_barrier
	s_add_u32 s38, s92, 0xff40000
	s_getreg_b32 s3, hwreg(HW_REG_XCC_ID, 0, 4)
	s_addc_u32 s39, s93, 0
	s_and_b32 s3, s3, 15
	s_lshl_b32 s42, s3, 6
	v_cmp_eq_u32_e64 s[8:9], 0, v210
	s_mov_b64 s[4:5], exec
	s_nop 0
	v_writelane_b32 v241, s8, 0
	s_nop 1
	v_writelane_b32 v241, s9, 1
	s_and_b64 s[8:9], s[4:5], s[8:9]
	s_mov_b64 exec, s[8:9]
	s_cbranch_execz .LBB0_5
	s_mov_b64 s[8:9], exec
	v_mbcnt_lo_u32_b32 v1, s8, 0
	v_mbcnt_hi_u32_b32 v1, s9, v1
	v_cmp_eq_u32_e32 vcc, 0, v1
	s_and_b64 s[10:11], exec, vcc
	s_mov_b64 exec, s[10:11]
	s_cbranch_execz .LBB0_5
	s_lshl_b32 s10, s42, 2
	s_bcnt1_i32_b64 s8, s[8:9]
	v_mov_b32_e32 v1, s10
	v_mov_b32_e32 v2, s8
	global_atomic_add v1, v2, s[38:39] offset:1024
	s_and_b32 s10, s2, 7
	s_lshl_b32 s10, 1, s10
	v_mov_b32_e32 v3, s10
	global_atomic_or v1, v3, s[38:39] offset:1028

; __device__ __forceinline__ void xcd_barrier(const XcdBarrier& b) {
;     asm volatile("s_waitcnt vmcnt(0)" ::: "memory");
;     __syncthreads();
;     if (threadIdx.x == 0) {
;         unsigned* bar = b.bar;
;         __builtin_amdgcn_s_waitcnt(0);
;         unsigned nloc = b.st[0], nx = b.st[1];
;         if (nloc == 0u) { xcd_barrier_complete(bar, b.x, nloc, nx); b.st[0] = nloc; b.st[1] = nx; }
.LBB0_205:
	s_waitcnt vmcnt(0)
	v_readlane_b32 s0, v241, 0
	v_readlane_b32 s1, v241, 1
	s_waitcnt vmcnt(0) lgkmcnt(0)
	s_barrier
	v_readfirstlane_b32 s100, v210
	s_nop 0
	s_lshr_b32 s100, s100, 6
	s_cmp_lg_u32 s100, 1
	s_cbranch_scc1 .Lbinv_2
	buffer_inv sc1
	s_waitcnt vmcnt(0)
	s_add_u32 s100, s92, 0xff40000
	s_addc_u32 s101, s93, 0
	v_mbcnt_lo_u32_b32 v0, -1, 0
	v_mbcnt_hi_u32_b32 v0, -1, v0
	v_and_b32_e32 v0, 15, v0
	v_lshlrev_b32_e32 v0, 8, v0
	global_load_dwordx2 v[2:3], v0, s[100:101] offset:1024 sc1
	s_waitcnt vmcnt(0)
	v_bcnt_u32_b32 v1, v3, 0
	v_cmp_eq_u32_e32 vcc, 32, v2
	s_nop 1
	s_mov_b64 s[100:101], vcc
	v_cmp_eq_u32_e32 vcc, 1, v1
	s_nop 1
	s_and_b64 s[100:101], s[100:101], vcc
	v_cmp_eq_u32_e32 vcc, 0, v2
	s_nop 1
	s_or_b64 s[100:101], s[100:101], vcc
	s_andn2_b64 s[100:101], exec, s[100:101]
	s_cmp_eq_u64 s[100:101], 0
	s_cselect_b32 s100, 1, 0
	v_mov_b32_e32 v0, 0x23030
	v_mov_b32_e32 v1, s100
	ds_write_b32 v0, v1
	s_waitcnt lgkmcnt(0)
.Lbinv_2:
	s_mov_b32 s99, 0
	s_and_saveexec_b64 s[16:17], s[0:1]
	s_cbranch_execz .LBB0_257
	s_add_i32 s3, 0, 0x23020
	v_mov_b32_e32 v0, s3
	s_waitcnt vmcnt(0) expcnt(0) lgkmcnt(0)
	ds_read_b32 v2, v0
	s_add_i32 s3, 0, 0x23024
	v_mov_b32_e32 v0, s3
	ds_read_b32 v0, v0
	s_waitcnt lgkmcnt(1)
	v_cmp_ne_u32_e32 vcc, 0, v2
	s_cbranch_vccnz .LBB0_221
	s_mov_b32 s3, 1
	v_mov_b32_e32 v16, 0
	s_branch .LBB0_209

; __device__ __forceinline__ unsigned xb_ld(unsigned* p)              { return __hip_atomic_load(p, __ATOMIC_RELAXED, __HIP_MEMORY_SCOPE_AGENT); }
; __device__ __forceinline__ unsigned xb_add(unsigned* p, unsigned v) { return __hip_atomic_fetch_add(p, v, __ATOMIC_RELAXED, __HIP_MEMORY_SCOPE_AGENT); }
; #define XB_SPIN(cond, bar) do { unsigned _sp = 0; while (cond) { __builtin_amdgcn_s_sleep(1); \
;     if ((++_sp & 255u) == 0u) { if (xb_ld(&(bar)[XB_TMO])) break; if (_sp > XB_SPIN_CAP) { atomicAdd(&(bar)[XB_TMO], 1u); break; } } } } while (0)
; __device__ __forceinline__ void xcd_barrier(const XcdBarrier& b) {
;     ...
;         const unsigned old = xb_add(&bar[XB_XSUB(b.x)], 1u);
;         const unsigned gen = old / nloc;
;         if (old + 1u == (gen + 1u) * nloc) {
;             __builtin_amdgcn_fence(__ATOMIC_RELEASE, "agent");
;             asm volatile("s_waitcnt vmcnt(0)" ::: "memory");
;             const unsigned og = xb_add(&bar[XB_TOP], 1u);
;             const unsigned tg = og / nx;
;             if (og + 1u == (tg + 1u) * nx) xb_add(&bar[XB_TOPGEN], 1u);
;             else XB_SPIN(xb_ld(&bar[XB_TOPGEN]) == tg, bar);
;             __builtin_amdgcn_fence(__ATOMIC_ACQUIRE, "agent");
;             xb_add(&bar[XB_XGEN(b.x)], 1u);
;             asm volatile("s_waitcnt vmcnt(0)" ::: "memory");
;         } else {
;             XB_SPIN(xb_ld(&bar[XB_XGEN(b.x)]) == gen, bar);
.LBB0_223:
	s_or_b64 exec, exec, s[18:19]
	v_cvt_f32_u32_e32 v4, v2
	s_waitcnt vmcnt(0)
	v_readfirstlane_b32 s3, v3
	v_sub_u32_e32 v3, 0, v2
	v_rcp_iflag_f32_e32 v4, v4
	v_add_u32_e32 v5, s3, v1
	v_mul_f32_e32 v4, 0x4f7ffffe, v4
	v_cvt_u32_f32_e32 v4, v4
	v_mul_lo_u32 v1, v3, v4
	v_mul_hi_u32 v1, v4, v1
	v_add_u32_e32 v1, v4, v1
	v_mul_hi_u32 v1, v5, v1
	v_mul_lo_u32 v3, v1, v2
	v_sub_u32_e32 v3, v5, v3
	v_add_u32_e32 v4, 1, v1
	v_cmp_ge_u32_e32 vcc, v3, v2
	s_nop 1
	v_cndmask_b32_e32 v1, v1, v4, vcc
	v_sub_u32_e32 v4, v3, v2
	v_cndmask_b32_e32 v3, v3, v4, vcc
	v_add_u32_e32 v4, 1, v1
	v_cmp_ge_u32_e32 vcc, v3, v2
	v_add_u32_e32 v3, 1, v5
	s_nop 0
	v_cndmask_b32_e32 v1, v1, v4, vcc
	v_mul_lo_u32 v4, v2, v1
	v_add_u32_e32 v2, v4, v2
	v_cmp_ne_u32_e32 vcc, v3, v2
	s_and_saveexec_b64 s[18:19], vcc
	s_xor_b64 s[18:19], exec, s[18:19]
	s_cbranch_execz .LBB0_237
	v_readlane_b32 s0, v240, 14
	s_waitcnt lgkmcnt(0)
	v_mov_b32_e32 v0, 0
	v_readlane_b32 s1, v240, 15
	s_nop 4
	v_readfirstlane_b32 s98, v1
	s_mov_b32 s99, 1
	v_cmp_ne_u32_e32 vcc, v1, v1
	s_and_saveexec_b64 s[22:23], vcc
	s_cbranch_execz .LBB0_236
	s_mov_b32 s3, 1
	s_mov_b64 s[24:25], 0
	s_branch .LBB0_227

; __device__ __forceinline__ int opaque_tid() { int t = threadIdx.x; asm volatile("" : "+v"(t)); return t; }
; #define LAS __attribute__((address_space(3)))
;     __host__ __device__ bool next(int i, Unit& u) const {
;         const long L = (long)i * G + c; if (L >= nwg) return false;
;         int wgid = (int)L; { const int q = nwg / NXCD, r = nwg % NXCD, xcd = wgid % NXCD, off = wgid / NXCD; wgid = (xcd < r ? xcd * (q + 1) : r * (q + 1) + (xcd - r) * q) + off; }
;         const int nig = WGM * nN, gid = wgid / nig, fm = gid * WGM, gsz = (nM - fm) < WGM ? (nM - fm) : WGM;
;         u.pm = fm + ((wgid % nig) % gsz); u.pn = (wgid % nig) / gsz; return true;
; __device__ __forceinline__ void p0b_mlp_weights(const Args& a, LAS unsigned char* lds) {
;     const int tid = opaque_tid(), lane = tid & 63, wave = tid >> 6;
;     LAS float* scr = (LAS float*)(lds + wave * 16640);
;     const int gw = blockIdx.x * NWAVES + wave, NGW = gridDim.x * NWAVES;
;     constexpr int I_UP = (D_ / 64) * (FF / 64), I_DN = (FF / 64) * (D_ / 64);
;     for (int it = gw; it < I_UP + I_DN; it += NGW) {
;         if (it < I_UP) transpose_item(a.w_up, D_, FF, (bf16*)(a.ws + WS_WUP), a.ln_mlp_g, scr, it, FF / 64, lane);
;         else transpose_item(a.w_dn, FF, D_, (bf16*)(a.ws + WS_WDN), nullptr, scr, it - I_UP, D_ / 64, lane);
.LBB0_257:
	s_or_b64 exec, exec, s[16:17]
	s_add_u32 s16, s92, 0x4000000
	s_addc_u32 s17, s93, 0
	s_ashr_i32 s3, s2, 31
	s_lshr_b32 s18, s3, 29
	s_add_i32 s18, s2, s18
	s_ashr_i32 s0, s18, 3
	s_and_b32 s18, s18, -8
	s_ashr_i32 s95, s94, 31
	s_sub_i32 s7, s2, s18
	s_cmp_lt_i32 s7, 0
	v_writelane_b32 v240, s0, 20
	s_cselect_b64 s[0:1], -1, 0
	v_writelane_b32 v240, s0, 21
	s_cmp_gt_i32 s7, -1
	v_mov_b32_e32 v18, v210
	v_writelane_b32 v240, s1, 22
	s_cselect_b64 s[0:1], -1, 0
	v_writelane_b32 v240, s0, 23
	s_waitcnt lgkmcnt(0)
	s_barrier
	v_writelane_b32 v130, s0, 0
	v_writelane_b32 v130, s10, 1
	v_writelane_b32 v130, s11, 2
	v_writelane_b32 v130, s20, 3
	v_writelane_b32 v130, s21, 4
	v_writelane_b32 v130, s22, 5
	v_writelane_b32 v130, s23, 6
	v_writelane_b32 v130, s24, 7
	v_writelane_b32 v130, s25, 8
	v_writelane_b32 v130, s26, 9
	v_writelane_b32 v130, s42, 10
	v_writelane_b32 v130, s43, 11
	v_writelane_b32 v130, s44, 12
	v_writelane_b32 v130, s45, 13
	v_writelane_b32 v130, s50, 14
	v_writelane_b32 v130, s51, 15
	v_writelane_b32 v130, s64, 16
	v_writelane_b32 v130, s65, 17
	v_writelane_b32 v130, s66, 18
	v_writelane_b32 v130, s67, 19
	v_writelane_b32 v130, s68, 20
	v_writelane_b32 v130, s69, 21
	v_writelane_b32 v130, s70, 22
	v_writelane_b32 v130, s71, 23
	v_writelane_b32 v130, s72, 24
	v_writelane_b32 v130, s73, 25
	v_writelane_b32 v130, s74, 26
	v_writelane_b32 v130, s75, 27
	v_writelane_b32 v130, s76, 28
	v_writelane_b32 v130, s77, 29
	v_writelane_b32 v130, s78, 30
	v_writelane_b32 v130, s79, 31
	v_writelane_b32 v130, s33, 32
	v_writelane_b32 v130, s40, 33
	s_movk_i32 s40, 0x200
	s_mov_b32 s33, 0x8000
	s_add_u32 s10, s92, 0xf6a0000
	v_mov_b32_e32 v0, v210
	s_addc_u32 s11, s93, 0
	v_readlane_b32 s0, v241, 19
	v_ashrrev_i32_e32 v1, 6, v0
	s_add_u32 s50, s92, 0xeea0000
	v_add_u32_e32 v84, s0, v1
	v_add_u32_e32 v84, 0xfffffa00, v84
	s_movk_i32 s20, 0x400
	s_addc_u32 s51, s93, 0
	v_cmp_gt_u32_e32 vcc, s20, v84
	s_and_saveexec_b64 s[20:21], vcc
	v_readlane_b32 s64, v241, 2
	v_readlane_b32 s72, v241, 10
	v_readlane_b32 s73, v241, 11
	v_readlane_b32 s74, v241, 12
	v_readlane_b32 s75, v241, 13
	v_readlane_b32 s76, v241, 14
	v_readlane_b32 s77, v241, 15
	v_readlane_b32 s78, v241, 16
	v_readlane_b32 s79, v241, 17
	v_readlane_b32 s65, v241, 3
	v_readlane_b32 s66, v241, 4
	v_readlane_b32 s67, v241, 5
	v_readlane_b32 s68, v241, 6
	v_readlane_b32 s69, v241, 7
	v_readlane_b32 s70, v241, 8
	v_readlane_b32 s71, v241, 9
	s_cbranch_execz .Lw5_554
	s_movk_i32 s24, 0x4100
	v_mul_lo_u32 v2, v1, s24
	v_add_u32_e32 v3, 0, v2
	v_bfe_u32 v85, v0, 4, 2
	v_lshlrev_b32_e32 v2, 2, v0
	v_bfe_u32 v87, v0, 3, 3
	v_lshlrev_b32_e32 v0, 3, v0
	v_and_b32_e32 v6, 56, v0
	v_and_b32_e32 v86, 60, v2
	v_mul_u32_u24_e32 v0, 0x104, v6
	v_lshlrev_b32_e32 v7, 2, v87
	v_lshlrev_b32_e32 v2, 2, v86
	v_add3_u32 v88, v3, v0, v7
	v_mov_b32_e32 v0, 0
	v_readlane_b32 s0, v241, 18
	v_add_u32_e32 v4, v3, v2
	v_mul_u32_u24_e32 v5, 0x104, v85
	v_mov_b32_e32 v3, v0
	v_lshl_add_u32 v96, v1, 6, s0
	v_add_u32_e32 v96, 0xfffe8000, v96
	v_lshlrev_b32_e32 v1, 2, v1
	s_cmp_lg_u64 s[72:73], 0
	v_lshl_add_u64 v[68:69], s[76:77], 0, v[2:3]
	v_lshl_add_u64 v[70:71], s[74:75], 0, v[2:3]
	v_lshlrev_b32_e32 v2, 1, v6
	v_lshl_add_u32 v1, s2, 5, v1
	v_add_u32_e32 v98, v4, v5
	s_mov_b64 s[22:23], 0
	s_cselect_b64 s[42:43], -1, 0
	v_or_b32_e32 v89, 8, v87
	v_or_b32_e32 v90, 16, v87
	v_or_b32_e32 v91, 24, v87
	v_or_b32_e32 v92, 32, v87
	v_or_b32_e32 v93, 40, v87
	v_or_b32_e32 v94, 48, v87
	v_or_b32_e32 v95, 56, v87
	v_lshl_add_u64 v[72:73], s[10:11], 0, v[2:3]
	v_lshl_add_u64 v[74:75], s[50:51], 0, v[2:3]
	v_add_u32_e32 v97, 0x3d800, v1
	s_movk_i32 s26, 0x800
	v_add_u32_e32 v99, 0x410, v98
	v_add_u32_e32 v100, 0x418, v98
	v_add_u32_e32 v101, 0x820, v98
	v_add_u32_e32 v102, 0x828, v98
	v_add_u32_e32 v103, 0xc30, v98
	v_add_u32_e32 v104, 0xc38, v98
	v_add_u32_e32 v105, 0x1040, v98
	v_add_u32_e32 v106, 0x1048, v98
	v_add_u32_e32 v107, 0x1450, v98
	v_add_u32_e32 v108, 0x1458, v98
	v_add_u32_e32 v109, 0x1860, v98
	v_add_u32_e32 v110, 0x1868, v98
	v_add_u32_e32 v111, 0x1c70, v98
	v_add_u32_e32 v112, 0x1c78, v98
	v_add_u32_e32 v113, 0x2080, v98
	v_add_u32_e32 v114, 0x2088, v98
	v_add_u32_e32 v115, 0x2490, v98
	v_add_u32_e32 v116, 0x2498, v98
	v_add_u32_e32 v117, 0x28a0, v98
	v_add_u32_e32 v118, 0x28a8, v98
	v_add_u32_e32 v119, 0x2cb0, v98
	v_add_u32_e32 v120, 0x2cb8, v98
	v_add_u32_e32 v121, 0x30c0, v98
	v_add_u32_e32 v122, 0x30c8, v98
	v_add_u32_e32 v123, 0x34d0, v98
	s_branch .Lw5_517

; __device__ __forceinline__ unsigned xb_ld(unsigned* p)              { return __hip_atomic_load(p, __ATOMIC_RELAXED, __HIP_MEMORY_SCOPE_AGENT); }
; #define XB_SPIN(cond, bar) do { unsigned _sp = 0; while (cond) { __builtin_amdgcn_s_sleep(1); \
;     if ((++_sp & 255u) == 0u) { if (xb_ld(&(bar)[XB_TMO])) break; if (_sp > XB_SPIN_CAP) { atomicAdd(&(bar)[XB_TMO], 1u); break; } } } } while (0)
; __device__ __forceinline__ void transpose_item(const float* W, int K, int N, bf16* WT, const float* gain, LAS float* scr, int item, int nblk, int lane) {
;     ...
;     if (gain) {
; #pragma unroll
;         for (int i = 0; i < 16; ++i) v[i] = v[i] * gain[k0 + 4 * i + kr]; }
; __device__ __forceinline__ void xcd_barrier(const XcdBarrier& b) {
;     ...
;             XB_SPIN(xb_ld(&bar[XB_XGEN(b.x)]) == gen, bar);
;             __builtin_amdgcn_fence(__ATOMIC_ACQUIRE, "agent");
;             asm volatile("s_waitcnt vmcnt(0)" ::: "memory");
.Lw5_552:
	s_or_b64 exec, exec, s[24:25]
	s_and_b64 vcc, exec, s[42:43]
	s_cbranch_vccz .Lw5_515
	v_lshl_add_u64 v[2:3], v[78:79], 2, s[72:73]
	global_load_dword v138, v[2:3], off
	global_load_dword v140, v[2:3], off offset:16
	global_load_dword v142, v[2:3], off offset:32
	global_load_dword v144, v[2:3], off offset:48
	global_load_dword v146, v[2:3], off offset:64
	global_load_dword v148, v[2:3], off offset:80
	global_load_dword v150, v[2:3], off offset:96
	global_load_dword v152, v[2:3], off offset:112
	global_load_dword v154, v[2:3], off offset:128
	global_load_dword v156, v[2:3], off offset:144
	global_load_dword v158, v[2:3], off offset:160
	global_load_dword v160, v[2:3], off offset:176
	global_load_dword v162, v[2:3], off offset:192
	global_load_dword v164, v[2:3], off offset:208
	global_load_dword v166, v[2:3], off offset:224
	global_load_dword v168, v[2:3], off offset:240
	s_waitcnt vmcnt(0)
	v_pk_mul_f32 v[10:11], v[10:11], v[138:139] op_sel_hi:[1,0]
	v_pk_mul_f32 v[8:9], v[8:9], v[138:139] op_sel_hi:[1,0]
	v_pk_mul_f32 v[6:7], v[6:7], v[140:141] op_sel_hi:[1,0]
	v_pk_mul_f32 v[4:5], v[4:5], v[140:141] op_sel_hi:[1,0]
	v_pk_mul_f32 v[14:15], v[14:15], v[142:143] op_sel_hi:[1,0]
	v_pk_mul_f32 v[12:13], v[12:13], v[142:143] op_sel_hi:[1,0]
	v_pk_mul_f32 v[18:19], v[18:19], v[144:145] op_sel_hi:[1,0]
	v_pk_mul_f32 v[16:17], v[16:17], v[144:145] op_sel_hi:[1,0]
	v_pk_mul_f32 v[22:23], v[22:23], v[146:147] op_sel_hi:[1,0]
	v_pk_mul_f32 v[20:21], v[20:21], v[146:147] op_sel_hi:[1,0]
	v_pk_mul_f32 v[26:27], v[26:27], v[148:149] op_sel_hi:[1,0]
	v_pk_mul_f32 v[24:25], v[24:25], v[148:149] op_sel_hi:[1,0]
	v_pk_mul_f32 v[30:31], v[30:31], v[150:151] op_sel_hi:[1,0]
	v_pk_mul_f32 v[28:29], v[28:29], v[150:151] op_sel_hi:[1,0]
	v_pk_mul_f32 v[34:35], v[34:35], v[152:153] op_sel_hi:[1,0]
	v_pk_mul_f32 v[32:33], v[32:33], v[152:153] op_sel_hi:[1,0]
	v_pk_mul_f32 v[38:39], v[38:39], v[154:155] op_sel_hi:[1,0]
	v_pk_mul_f32 v[36:37], v[36:37], v[154:155] op_sel_hi:[1,0]
	v_pk_mul_f32 v[42:43], v[42:43], v[156:157] op_sel_hi:[1,0]
	v_pk_mul_f32 v[40:41], v[40:41], v[156:157] op_sel_hi:[1,0]
	v_pk_mul_f32 v[46:47], v[46:47], v[158:159] op_sel_hi:[1,0]
	v_pk_mul_f32 v[44:45], v[44:45], v[158:159] op_sel_hi:[1,0]
	v_pk_mul_f32 v[50:51], v[50:51], v[160:161] op_sel_hi:[1,0]
	v_pk_mul_f32 v[48:49], v[48:49], v[160:161] op_sel_hi:[1,0]
	v_pk_mul_f32 v[54:55], v[54:55], v[162:163] op_sel_hi:[1,0]
	v_pk_mul_f32 v[52:53], v[52:53], v[162:163] op_sel_hi:[1,0]
	v_pk_mul_f32 v[58:59], v[58:59], v[164:165] op_sel_hi:[1,0]
	v_pk_mul_f32 v[56:57], v[56:57], v[164:165] op_sel_hi:[1,0]
	v_pk_mul_f32 v[62:63], v[62:63], v[166:167] op_sel_hi:[1,0]
	v_pk_mul_f32 v[60:61], v[60:61], v[166:167] op_sel_hi:[1,0]
	v_pk_mul_f32 v[66:67], v[66:67], v[168:169] op_sel_hi:[1,0]
	v_pk_mul_f32 v[64:65], v[64:65], v[168:169] op_sel_hi:[1,0]
	s_branch .Lw5_515
.Lw5_554:
	s_or_b64 exec, exec, s[20:21]
	v_readlane_b32 s0, v130, 0
	v_readlane_b32 s10, v130, 1
	v_readlane_b32 s11, v130, 2
	v_readlane_b32 s20, v130, 3
	v_readlane_b32 s21, v130, 4
	v_readlane_b32 s22, v130, 5
	v_readlane_b32 s23, v130, 6
	v_readlane_b32 s24, v130, 7
	v_readlane_b32 s25, v130, 8
	v_readlane_b32 s26, v130, 9
	v_readlane_b32 s42, v130, 10
	v_readlane_b32 s43, v130, 11
	v_readlane_b32 s44, v130, 12
	v_readlane_b32 s45, v130, 13
	v_readlane_b32 s50, v130, 14
	v_readlane_b32 s51, v130, 15
	v_readlane_b32 s64, v130, 16
	v_readlane_b32 s65, v130, 17
	v_readlane_b32 s66, v130, 18
	v_readlane_b32 s67, v130, 19
	v_readlane_b32 s68, v130, 20
	v_readlane_b32 s69, v130, 21
	v_readlane_b32 s70, v130, 22
	v_readlane_b32 s71, v130, 23
	v_readlane_b32 s72, v130, 24
	v_readlane_b32 s73, v130, 25
	v_readlane_b32 s74, v130, 26
	v_readlane_b32 s75, v130, 27
	v_readlane_b32 s76, v130, 28
	v_readlane_b32 s77, v130, 29
	v_readlane_b32 s78, v130, 30
	v_readlane_b32 s79, v130, 31
	v_readlane_b32 s33, v130, 32
	v_readlane_b32 s40, v130, 33
	s_cmp_eq_u32 s99, 0
	s_cbranch_scc1 .Lgb2_done
	v_readlane_b32 s100, v240, 14
	v_readlane_b32 s101, v240, 15
	s_mov_b32 s99, 0
	s_nop 3

; #define PG8_WAIT_V(n) asm volatile("s_waitcnt vmcnt(" #n ")" ::: "memory")
; #define PG8_BAR __builtin_amdgcn_s_barrier()
; template <class Epi, class Sched, bool ALIGN_EPI = false, bool SP2 = false>
; __device__ __forceinline__ void gemm_phase(PG8_LAS unsigned char* lds, const Gemm g, const Sched& S, const Epi& E) {
;     ...
;     for (int i = 0; i < 2; ++i) { int R, C; stage_rc(tid * 16 + i * 8192, R, C); const int Rb = Epi::PERM ? ((R & ~31) + perm32(R & 31)) : R;
;         voffA[i] = (unsigned)(R * g.lda + C) * 2u; voffB[i] = (unsigned)(Rb * K + C) * 2u; }
;     const size_t kstep = (size_t)(BK * 2);
;     const size_t hstepB = (size_t)HALF * K * 2, hstepA = (size_t)HALF * g.lda * 2;
;     const size_t tstepB = 2 * hstepB, tstepA = 2 * hstepA;
;     const unsigned ldsw = (unsigned)wid * 1024u;
;     const int aoff = lds_byte(wr * 64 + fr, fq * 8), boff = lds_byte(wc * 32 + fr, fq * 8);
;     ...
;     Unit cur, nxt; int ui = 0;
;     if (!S.next(0, cur)) return;
;     f32x4 acc[2][2][4][2];
; #pragma unroll
;     for (int a = 0; a < 2; ++a)
; #pragma unroll
;         for (int b = 0; b < 2; ++b)
; #pragma unroll
;             for (int m = 0; m < 4; ++m)
; #pragma unroll
;                 for (int n = 0; n < 2; ++n) acc[a][b][m][n] = (f32x4){0.f, 0.f, 0.f, 0.f};
;     bf16x8 At[4][2], B0[2][2], B1[2][2];
;     const char* cA = (const char*)g.A + (size_t)cur.pm * tstepA; const char* cB = (const char*)g.Bt + (size_t)cur.pn * tstepB;
;     S.a_ready(cur);
;     if constexpr (SP2) {
;         PG8_STAGE(PG8_SB(0, 0), cB, voffB); PG8_STAGE(PG8_SB(0, 1), cB + hstepB, voffB); PG8_STAGE(PG8_SA(0, 0), cA, voffA); PG8_STAGE(PG8_SA(0, 1), cA + hstepA, voffA);
;         if (wr == 1) PG8_BAR;
;         PG8_WAIT_V(2); PG8_BAR;
;         PG8_STAGE(PG8_SB(1, 0), cB + kstep, voffB); PG8_STAGE(PG8_SA(1, 0), cA + kstep, voffA); PG8_STAGE(PG8_SB(1, 1), cB + hstepB + kstep, voffB);
;         PG8_WAIT_V(6); PG8_BAR;
;     } else {
;         PG8_STAGE(PG8_SB(0, 0), cB, voffB); PG8_STAGE(PG8_SA(0, 0), cA, voffA); PG8_STAGE(PG8_SB(0, 1), cB + hstepB, voffB); PG8_STAGE(PG8_SA(0, 1), cA + hstepA, voffA);
;         if (wr == 1) PG8_BAR;
;         PG8_WAIT_V(4); PG8_BAR;
;         PG8_STAGE(PG8_SB(1, 0), cB + kstep, voffB); PG8_STAGE(PG8_SA(1, 0), cA + kstep, voffA); PG8_STAGE(PG8_SB(1, 1), cB + hstepB + kstep, voffB);
;         PG8_WAIT_V(6); PG8_BAR;
.Lgb2_done:
	v_mov_b32_e32 v18, v210
	s_waitcnt vmcnt(0) lgkmcnt(0)
	s_barrier
	v_writelane_b32 v240, s1, 24
	s_cmpk_lt_i32 s2, 0xc0
	s_movk_i32 s38, 0x100
	v_readfirstlane_b32 s25, v18
	v_writelane_b32 v240, s7, 25
	s_cbranch_scc0 .LBB0_276
	v_lshlrev_b32_e32 v0, 4, v18
	v_add_u32_e32 v1, 0x2000, v0
	v_ashrrev_i32_e32 v2, 31, v1
	v_lshrrev_b32_e32 v2, 22, v2
	v_add_u32_e32 v2, v1, v2
	v_ashrrev_i32_e32 v12, 10, v2
	v_mul_i32_i24_e32 v2, 0x400, v12
	v_sub_u32_e32 v1, v1, v2
	v_lshrrev_b32_e32 v2, 4, v1
	v_bitop3_b32 v1, v2, v1, 32 bitop3:0x6c
	v_ashrrev_i32_e32 v2, 31, v1
	v_lshrrev_b32_e32 v2, 26, v2
	v_add_u32_e32 v2, v1, v2
	v_lshlrev_b32_e32 v3, 3, v12
	v_ashrrev_i32_e32 v13, 6, v2
	v_and_b32_e32 v3, -16, v3
	v_add_u32_e32 v3, v13, v3
	v_and_b32_e32 v4, 3, v13
	s_mov_b32 s24, 0x7fffffe0
	v_lshrrev_b32_e32 v5, 2, v3
	v_lshlrev_b32_e32 v6, 1, v3
	v_and_b32_e32 v2, 0xc0, v2
	v_and_or_b32 v4, v3, s24, v4
	v_and_b32_e32 v5, 4, v5
	v_and_b32_e32 v6, 24, v6
	v_sub_u32_e32 v1, v1, v2
	v_mov_b32_e32 v2, 1
	v_or3_b32 v4, v4, v5, v6
	v_lshlrev_b32_e32 v5, 5, v12
	v_ashrrev_i16_sdwa v1, v2, sext(v1) dst_sel:DWORD dst_unused:UNUSED_PAD src0_sel:DWORD src1_sel:BYTE_0
	v_and_b32_e32 v5, 32, v5
	v_bfe_i32 v14, v1, 0, 16
	v_mul_lo_u32 v4, v4, s38
	v_add_u32_e32 v1, v5, v14
	v_lshlrev_b32_e32 v3, 12, v3
	v_add_lshl_u32 v128, v4, v1, 1
	v_lshl_add_u32 v130, v1, 1, v3
	v_bfe_i32 v1, v18, 27, 1
	v_lshrrev_b32_e32 v1, 22, v1
	v_add_u32_e32 v1, v0, v1
	v_and_b32_e32 v1, 0xfffffc00, v1
	v_sub_u32_e32 v0, v0, v1
	v_lshrrev_b32_e32 v1, 4, v0
	v_bitop3_b32 v1, v1, v0, 32 bitop3:0x6c
	v_ashrrev_i32_e32 v0, 31, v0
	v_lshrrev_b32_e32 v0, 26, v0
	v_add_u32_e32 v0, v1, v0
	v_ashrrev_i32_e32 v15, 6, v0
	v_ashrrev_i32_e32 v0, 31, v18
	v_lshrrev_b32_e32 v0, 26, v0
	v_add_u32_e32 v0, v18, v0
	s_add_u32 s41, s92, 0xec00000
	v_ashrrev_i32_e32 v16, 6, v0
	s_addc_u32 s64, s93, 0
	s_ashr_i32 s31, s25, 6
	s_ashr_i32 s39, s38, 31
	v_lshlrev_b32_e32 v0, 3, v16
	v_readlane_b32 s26, v240, 21
	s_ashr_i32 s42, s25, 8
	s_lshl_b64 s[18:19], s[38:39], 8
	s_lshl_b64 s[22:23], s[38:39], 9
	s_lshl_b32 s65, s31, 10
	v_and_b32_e32 v0, -16, v0
	v_readlane_b32 s27, v240, 22
	v_add_u32_e32 v0, v15, v0
	v_and_b32_e32 v3, 3, v15
	s_and_b64 s[26:27], s[26:27], exec
	v_and_or_b32 v3, v0, s24, v3
	s_cselect_b32 s24, 25, 24
	s_mul_i32 s24, s7, s24
	v_readlane_b32 s7, v240, 20
	s_add_i32 s24, s24, s7
	s_mul_hi_i32 s26, s24, 0x2aaaaaab
	s_lshr_b32 s27, s26, 31
	s_ashr_i32 s26, s26, 1
	s_add_i32 s26, s26, s27
	s_lshl_b32 s27, s26, 2
	s_mul_i32 s26, s26, 12
	s_sub_i32 s26, s24, s26
	s_bfe_i32 s24, s26, 0x80000
	s_bfe_u32 s24, s24, 0x2000d
	s_add_i32 s28, s26, s24
	s_bfe_i32 s24, s28, 0x80000
	s_and_b32 s28, s28, 0xfc
	s_sext_i32_i16 s30, s24
	s_sub_i32 s26, s26, s28
	s_lshr_b32 s24, s30, 2
	s_sext_i32_i8 s26, s26
	v_lshrrev_b32_e32 v4, 2, v0
	v_lshlrev_b32_e32 v5, 1, v0
	s_add_i32 s48, s27, s26
	s_bfe_i64 s[26:27], s[24:25], 0x100000
	s_ashr_i32 s30, s30, 2
	v_and_b32_e32 v4, 4, v4
	v_and_b32_e32 v5, 24, v5
	s_mul_hi_u32 s26, s22, s30
	s_mul_i32 s27, s22, s27
	s_mov_b64 s[90:91], s[34:35]
	v_or3_b32 v3, v3, v4, v5
	v_mul_i32_i24_e32 v5, 64, v15
	s_add_i32 s34, s26, s27
	s_lshr_b64 s[26:27], s[38:39], 23
	v_sub_u32_e32 v1, v1, v5
	s_ashr_i32 s49, s48, 31
	s_mul_i32 s26, s26, s30
	v_lshlrev_b32_e32 v4, 5, v16
	v_ashrrev_i16_sdwa v1, v2, sext(v1) dst_sel:DWORD dst_unused:UNUSED_PAD src0_sel:DWORD src1_sel:BYTE_0
	s_lshl_b64 s[28:29], s[48:49], 20
	s_add_i32 s34, s34, s26
	s_mul_i32 s26, s22, s30
	v_and_b32_e32 v4, 32, v4
	v_bfe_i32 v17, v1, 0, 16
	s_add_u32 s60, s41, s26
	v_mul_lo_u32 v3, v3, s38
	v_add_u32_e32 v1, v4, v17
	s_addc_u32 s61, s64, s34
	s_add_i32 s26, s65, 0
	v_add_lshl_u32 v132, v3, v1, 1
	s_add_i32 m0, s26, 0x10000
	s_mov_b64 s[4:5], s[62:63]
	global_load_lds_dwordx4 v132, s[60:61]
	s_add_i32 m0, s26, 0x12000
	s_add_u32 s34, s60, s18
	global_load_lds_dwordx4 v128, s[60:61]
	s_addc_u32 s35, s61, s19
	s_add_i32 m0, s26, 0x14000
	v_mov_b32_e32 v133, 0
	global_load_lds_dwordx4 v132, s[34:35]
	s_add_i32 m0, s26, 0x16000
	s_add_u32 s62, s92, s28
	v_lshlrev_b32_e32 v0, 12, v0
	v_mov_b32_e32 v129, v133
	s_addc_u32 s63, s93, s29
	s_add_i32 s27, s26, 0x2000
	v_lshl_add_u32 v134, v1, 1, v0
	v_lshl_add_u64 v[4:5], s[34:35], 0, v[132:133]
	v_lshl_add_u64 v[6:7], s[34:35], 0, v[128:129]
	global_load_lds_dwordx4 v128, s[34:35]
	s_mov_b32 m0, s26
	s_add_u32 s34, s62, 0x80000
	global_load_lds_dwordx4 v134, s[62:63]
	s_mov_b32 m0, s27
	s_addc_u32 s35, s63, 0
	s_add_i32 s28, s26, 0x4000
	global_load_lds_dwordx4 v130, s[62:63]
	s_mov_b32 m0, s28
	s_add_i32 s29, s26, 0x6000
	global_load_lds_dwordx4 v134, s[34:35]
	s_mov_b32 m0, s29
	v_mov_b32_e32 v135, v133
	global_load_lds_dwordx4 v130, s[34:35]
	v_mov_b32_e32 v131, v133
	s_cmp_eq_u32 s42, 1
	s_mov_b64 s[0:1], s[88:89]
	v_lshl_add_u64 v[0:1], s[60:61], 0, v[132:133]
	v_lshl_add_u64 v[2:3], s[60:61], 0, v[128:129]
	v_lshl_add_u64 v[8:9], s[62:63], 0, v[134:135]
	v_lshl_add_u64 v[10:11], s[62:63], 0, v[130:131]
	s_cselect_b64 s[46:47], -1, 0
	s_cmp_lg_u32 s42, 1
	s_cbranch_scc1 .LBB0_260
	s_barrier

; __device__ __forceinline__ int opaque_tid() { int t = threadIdx.x; asm volatile("" : "+v"(t)); return t; }
; #define LAS __attribute__((address_space(3)))
; __device__ __forceinline__ void p0b_mlp_weights(const Args& a, LAS unsigned char* lds) {
;     const int tid = opaque_tid(), lane = tid & 63, wave = tid >> 6;
;     LAS float* scr = (LAS float*)(lds + wave * 16640);
;     const int gw = blockIdx.x * NWAVES + wave, NGW = gridDim.x * NWAVES;
;     constexpr int I_UP = (D_ / 64) * (FF / 64), I_DN = (FF / 64) * (D_ / 64);
;     for (int it = gw; it < I_UP + I_DN; it += NGW) {
;         if (it < I_UP) transpose_item(a.w_up, D_, FF, (bf16*)(a.ws + WS_WUP), a.ln_mlp_g, scr, it, FF / 64, lane);
;         else transpose_item(a.w_dn, FF, D_, (bf16*)(a.ws + WS_WDN), nullptr, scr, it - I_UP, D_ / 64, lane);
; __global__ void __launch_bounds__(NTHREADS, 2) fwd_megakernel(Args a) {
;     ...
;         float mq = 0.f, mk = 0.f;
;         for (int i = 0; i < 96; ++i) { mq = fmaxf(mq, fabsf(a.q_norm_g[i])); mk = fmaxf(mk, fabsf(a.k_norm_g[i])); }
;         const float mb = fminf(96.f * mq * mk * 0.10206207261596577f * LOG2E, 80.f);
.LBB0_512:
	s_add_u32 s20, s72, s10
	s_addc_u32 s21, s73, s11
	global_load_dwordx4 v[2:5], v0, s[20:21] offset:32
	global_load_dwordx4 v[6:9], v0, s[20:21] offset:16
	global_load_dwordx4 v[10:13], v0, s[20:21]
	s_add_u32 s20, s74, s10
	s_addc_u32 s21, s75, s11
	global_load_dwordx4 v[14:17], v0, s[20:21]
	global_load_dwordx4 v[18:21], v0, s[20:21] offset:16
	global_load_dwordx4 v[22:25], v0, s[20:21] offset:32
	s_add_u32 s10, s10, 48
	s_addc_u32 s11, s11, 0
	s_cmpk_eq_i32 s10, 0x180
	s_waitcnt vmcnt(3)
	v_max3_f32 v1, v82, |v10|, |v11|
	v_max3_f32 v1, v1, |v12|, |v13|
	s_waitcnt vmcnt(2)
	v_max3_f32 v10, v83, |v14|, |v15|
	v_max3_f32 v1, v1, |v6|, |v7|
	v_max3_f32 v6, v10, |v16|, |v17|
	v_max3_f32 v1, v1, |v8|, |v9|
	s_waitcnt vmcnt(1)
	v_max3_f32 v6, v6, |v18|, |v19|
	v_max3_f32 v1, v1, |v2|, |v3|
	v_max3_f32 v2, v6, |v20|, |v21|
	v_max3_f32 v82, v1, |v4|, |v5|
	s_waitcnt vmcnt(0)
	v_max3_f32 v1, v2, |v22|, |v23|
	v_max3_f32 v83, v1, |v24|, |v25|
	s_cbranch_scc0 .LBB0_512
	s_add_u32 s10, s92, 0xf6a0000
	v_mov_b32_e32 v0, v210
	s_addc_u32 s11, s93, 0
	v_readlane_b32 s0, v241, 19
	v_ashrrev_i32_e32 v1, 6, v0
	s_add_u32 s50, s92, 0xeea0000
	v_add_u32_e32 v84, s0, v1
	v_add_u32_e32 v84, 0x400, v84
	s_movk_i32 s20, 0x800
	s_addc_u32 s51, s93, 0
	v_cmp_gt_i32_e32 vcc, s20, v84
	s_and_saveexec_b64 s[20:21], vcc
	v_readlane_b32 s64, v241, 2
	v_readlane_b32 s72, v241, 10
	v_readlane_b32 s73, v241, 11
	v_readlane_b32 s74, v241, 12
	v_readlane_b32 s75, v241, 13
	v_readlane_b32 s76, v241, 14
	v_readlane_b32 s77, v241, 15
	v_readlane_b32 s78, v241, 16
	v_readlane_b32 s79, v241, 17
	v_readlane_b32 s65, v241, 3
	v_readlane_b32 s66, v241, 4
	v_readlane_b32 s67, v241, 5
	v_readlane_b32 s68, v241, 6
	v_readlane_b32 s69, v241, 7
	v_readlane_b32 s70, v241, 8
	v_readlane_b32 s71, v241, 9
	s_cbranch_execz .LBB0_554
	s_movk_i32 s24, 0x4100
	v_mul_lo_u32 v2, v1, s24
	v_add_u32_e32 v3, 0, v2
	v_bfe_u32 v85, v0, 4, 2
	v_lshlrev_b32_e32 v2, 2, v0
	v_bfe_u32 v87, v0, 3, 3
	v_lshlrev_b32_e32 v0, 3, v0
	v_and_b32_e32 v6, 56, v0
	v_and_b32_e32 v86, 60, v2
	v_mul_u32_u24_e32 v0, 0x104, v6
	v_lshlrev_b32_e32 v7, 2, v87
	v_lshlrev_b32_e32 v2, 2, v86
	v_add3_u32 v88, v3, v0, v7
	v_mov_b32_e32 v0, 0
	v_readlane_b32 s0, v241, 18
	v_add_u32_e32 v4, v3, v2
	v_mul_u32_u24_e32 v5, 0x104, v85
	v_mov_b32_e32 v3, v0
	v_lshl_add_u32 v96, v1, 6, s0
	v_add_u32_e32 v96, 0x10000, v96
	v_lshlrev_b32_e32 v1, 2, v1
	s_cmp_lg_u64 s[72:73], 0
	v_lshl_add_u64 v[68:69], s[76:77], 0, v[2:3]
	v_lshl_add_u64 v[70:71], s[74:75], 0, v[2:3]
	v_lshlrev_b32_e32 v2, 1, v6
	v_lshl_add_u32 v1, s2, 5, v1
	v_add_u32_e32 v98, v4, v5
	s_mov_b64 s[22:23], 0
	s_cselect_b64 s[42:43], -1, 0
	v_or_b32_e32 v89, 8, v87
	v_or_b32_e32 v90, 16, v87
	v_or_b32_e32 v91, 24, v87
	v_or_b32_e32 v92, 32, v87
	v_or_b32_e32 v93, 40, v87
	v_or_b32_e32 v94, 48, v87
	v_or_b32_e32 v95, 56, v87
	v_lshl_add_u64 v[72:73], s[10:11], 0, v[2:3]
	v_lshl_add_u64 v[74:75], s[50:51], 0, v[2:3]
	v_add_u32_e32 v97, 0x40000, v1
	s_lshl_b32 s26, s94, 5
	v_add_u32_e32 v99, 0x410, v98
	v_add_u32_e32 v100, 0x418, v98
	v_add_u32_e32 v101, 0x820, v98
	v_add_u32_e32 v102, 0x828, v98
	v_add_u32_e32 v103, 0xc30, v98
	v_add_u32_e32 v104, 0xc38, v98
	v_add_u32_e32 v105, 0x1040, v98
	v_add_u32_e32 v106, 0x1048, v98
	v_add_u32_e32 v107, 0x1450, v98
	v_add_u32_e32 v108, 0x1458, v98
	v_add_u32_e32 v109, 0x1860, v98
	v_add_u32_e32 v110, 0x1868, v98
	v_add_u32_e32 v111, 0x1c70, v98
	v_add_u32_e32 v112, 0x1c78, v98
	v_add_u32_e32 v113, 0x2080, v98
	v_add_u32_e32 v114, 0x2088, v98
	v_add_u32_e32 v115, 0x2490, v98
	v_add_u32_e32 v116, 0x2498, v98
	v_add_u32_e32 v117, 0x28a0, v98
	v_add_u32_e32 v118, 0x28a8, v98
	v_add_u32_e32 v119, 0x2cb0, v98
	v_add_u32_e32 v120, 0x2cb8, v98
	v_add_u32_e32 v121, 0x30c0, v98
	v_add_u32_e32 v122, 0x30c8, v98
	v_add_u32_e32 v123, 0x34d0, v98
	s_branch .LBB0_517

; __device__ __forceinline__ void xcd_barrier(const XcdBarrier& b) {
;     asm volatile("s_waitcnt vmcnt(0)" ::: "memory");
;     __syncthreads();
;     if (threadIdx.x == 0) {
;         unsigned* bar = b.bar;
;         __builtin_amdgcn_s_waitcnt(0);
;         unsigned nloc = b.st[0], nx = b.st[1];
;         if (nloc == 0u) { xcd_barrier_complete(bar, b.x, nloc, nx); b.st[0] = nloc; b.st[1] = nx; }
.Lbinv_6:
	s_and_saveexec_b64 s[0:1], s[4:5]
	v_readlane_b32 s16, v241, 2
	v_readlane_b32 s30, v241, 16
	v_readlane_b32 s31, v241, 17
	s_mov_b64 s[54:55], s[30:31]
	v_readlane_b32 s17, v241, 3
	v_readlane_b32 s18, v241, 4
	v_readlane_b32 s19, v241, 5
	v_readlane_b32 s20, v241, 6
	v_readlane_b32 s21, v241, 7
	v_readlane_b32 s22, v241, 8
	v_readlane_b32 s23, v241, 9
	v_readlane_b32 s24, v241, 10
	v_readlane_b32 s25, v241, 11
	v_readlane_b32 s26, v241, 12
	v_readlane_b32 s27, v241, 13
	v_readlane_b32 s28, v241, 14
	v_readlane_b32 s29, v241, 15
	s_cbranch_execz .LBB0_817
	s_add_i32 s8, 0, 0x23020
	v_mov_b32_e32 v0, s8
	s_waitcnt vmcnt(0) expcnt(0) lgkmcnt(0)
	ds_read_b32 v2, v0
	s_add_i32 s8, 0, 0x23024
	v_mov_b32_e32 v0, s8
	ds_read_b32 v0, v0
	s_waitcnt lgkmcnt(1)
	v_cmp_ne_u32_e32 vcc, 0, v2
	s_cbranch_vccnz .LBB0_781
	s_mov_b32 s20, 1
	v_mov_b32_e32 v16, 0
	s_branch .LBB0_769

; __device__ __forceinline__ unsigned xb_ld(unsigned* p)              { return __hip_atomic_load(p, __ATOMIC_RELAXED, __HIP_MEMORY_SCOPE_AGENT); }
; __device__ __forceinline__ unsigned xb_add(unsigned* p, unsigned v) { return __hip_atomic_fetch_add(p, v, __ATOMIC_RELAXED, __HIP_MEMORY_SCOPE_AGENT); }
; #define XB_SPIN(cond, bar) do { unsigned _sp = 0; while (cond) { __builtin_amdgcn_s_sleep(1); \
;     if ((++_sp & 255u) == 0u) { if (xb_ld(&(bar)[XB_TMO])) break; if (_sp > XB_SPIN_CAP) { atomicAdd(&(bar)[XB_TMO], 1u); break; } } } } while (0)
; __device__ __forceinline__ void xcd_barrier(const XcdBarrier& b) {
;     ...
;         if (old + 1u == (gen + 1u) * nloc) {
;             __builtin_amdgcn_fence(__ATOMIC_RELEASE, "agent");
;             asm volatile("s_waitcnt vmcnt(0)" ::: "memory");
;             const unsigned og = xb_add(&bar[XB_TOP], 1u);
;             const unsigned tg = og / nx;
;             if (og + 1u == (tg + 1u) * nx) xb_add(&bar[XB_TOPGEN], 1u);
;             else XB_SPIN(xb_ld(&bar[XB_TOPGEN]) == tg, bar);
.LBB0_797:
	s_andn2_saveexec_b64 s[8:9], s[8:9]
	s_cbranch_execz .LBB0_817
	v_mov_b32_e32 v3, 0x23030
	ds_read_b32 v3, v3
	s_waitcnt lgkmcnt(0)
	v_readfirstlane_b32 s100, v3
	s_nop 0
	s_cmp_lg_u32 s100, 0
	s_cbranch_scc1 .Lloc_6
	s_mov_b64 s[8:9], exec
	buffer_wbl2 sc1
	s_waitcnt lgkmcnt(0)
	s_waitcnt vmcnt(0)
	v_mbcnt_lo_u32_b32 v1, s8, 0
	v_mbcnt_hi_u32_b32 v1, s9, v1
	v_cmp_eq_u32_e32 vcc, 0, v1
	s_and_saveexec_b64 s[16:17], vcc
	s_cbranch_execz .LBB0_800
	s_bcnt1_i32_b64 s8, s[8:9]
	v_readlane_b32 s4, v240, 16
	v_mov_b32_e32 v2, 0
	v_mov_b32_e32 v3, s8
	v_readlane_b32 s5, v240, 17
	s_nop 4
	global_atomic_add v2, v2, v3, s[4:5] sc0

; __device__ __forceinline__ unsigned xb_add(unsigned* p, unsigned v) { return __hip_atomic_fetch_add(p, v, __ATOMIC_RELAXED, __HIP_MEMORY_SCOPE_AGENT); }
; __device__ __forceinline__ void xcd_barrier(const XcdBarrier& b) {
;     ...
;             xb_add(&bar[XB_XGEN(b.x)], 1u);
;             asm volatile("s_waitcnt vmcnt(0)" ::: "memory");
.Lloc_6:
	s_mov_b64 s[8:9], exec
	v_mbcnt_lo_u32_b32 v0, s8, 0
	v_mbcnt_hi_u32_b32 v0, s9, v0
	v_cmp_eq_u32_e32 vcc, 0, v0
	s_waitcnt vmcnt(0)
	s_and_saveexec_b64 s[16:17], vcc
	s_cbranch_execz .LBB0_816
	s_bcnt1_i32_b64 s8, s[8:9]
	v_readlane_b32 s4, v240, 14
	v_mov_b32_e32 v0, 0
	v_mov_b32_e32 v1, s8
	v_readlane_b32 s5, v240, 15
	s_nop 4
	global_atomic_add v0, v1, s[4:5]

; __device__ __forceinline__ unsigned xb_ld(unsigned* p)              { return __hip_atomic_load(p, __ATOMIC_RELAXED, __HIP_MEMORY_SCOPE_AGENT); }
; __device__ __forceinline__ unsigned xb_add(unsigned* p, unsigned v) { return __hip_atomic_fetch_add(p, v, __ATOMIC_RELAXED, __HIP_MEMORY_SCOPE_AGENT); }
; #define XB_SPIN(cond, bar) do { unsigned _sp = 0; while (cond) { __builtin_amdgcn_s_sleep(1); \
;     if ((++_sp & 255u) == 0u) { if (xb_ld(&(bar)[XB_TMO])) break; if (_sp > XB_SPIN_CAP) { atomicAdd(&(bar)[XB_TMO], 1u); break; } } } } while (0)
; __device__ __forceinline__ void xcd_barrier(const XcdBarrier& b) {
;     ...
;         if (old + 1u == (gen + 1u) * nloc) {
;             __builtin_amdgcn_fence(__ATOMIC_RELEASE, "agent");
;             asm volatile("s_waitcnt vmcnt(0)" ::: "memory");
;             const unsigned og = xb_add(&bar[XB_TOP], 1u);
;             const unsigned tg = og / nx;
;             if (og + 1u == (tg + 1u) * nx) xb_add(&bar[XB_TOPGEN], 1u);
;             else XB_SPIN(xb_ld(&bar[XB_TOPGEN]) == tg, bar);
.LBB0_876:
	s_andn2_saveexec_b64 s[4:5], s[4:5]
	s_cbranch_execz .LBB0_896
	v_mov_b32_e32 v3, 0x23030
	ds_read_b32 v3, v3
	s_waitcnt lgkmcnt(0)
	v_readfirstlane_b32 s100, v3
	s_nop 0
	s_cmp_lg_u32 s100, 0
	s_cbranch_scc1 .Lloc_7
	s_mov_b64 s[4:5], exec
	buffer_wbl2 sc1
	s_waitcnt lgkmcnt(0)
	s_waitcnt vmcnt(0)
	v_mbcnt_lo_u32_b32 v1, s4, 0
	v_mbcnt_hi_u32_b32 v1, s5, v1
	v_cmp_eq_u32_e32 vcc, 0, v1
	s_and_saveexec_b64 s[6:7], vcc
	s_cbranch_execz .LBB0_879
	s_bcnt1_i32_b64 s4, s[4:5]
	v_mov_b32_e32 v3, s4
	v_readlane_b32 s4, v240, 16
	v_mov_b32_e32 v2, 0
	v_readlane_b32 s5, v240, 17
	s_nop 4
	global_atomic_add v2, v2, v3, s[4:5] sc0

; __device__ __forceinline__ unsigned xb_add(unsigned* p, unsigned v) { return __hip_atomic_fetch_add(p, v, __ATOMIC_RELAXED, __HIP_MEMORY_SCOPE_AGENT); }
; __device__ __forceinline__ void xcd_barrier(const XcdBarrier& b) {
;     ...
;             xb_add(&bar[XB_XGEN(b.x)], 1u);
;             asm volatile("s_waitcnt vmcnt(0)" ::: "memory");
.Lloc_7:
	s_mov_b64 s[4:5], exec
	v_mbcnt_lo_u32_b32 v0, s4, 0
	v_mbcnt_hi_u32_b32 v0, s5, v0
	v_cmp_eq_u32_e32 vcc, 0, v0
	s_waitcnt vmcnt(0)
	s_and_saveexec_b64 s[6:7], vcc
	s_cbranch_execz .LBB0_895
	s_bcnt1_i32_b64 s4, s[4:5]
	v_mov_b32_e32 v1, s4
	v_readlane_b32 s4, v240, 14
	v_mov_b32_e32 v0, 0
	v_readlane_b32 s5, v240, 15
	s_nop 4
	global_atomic_add v0, v1, s[4:5]
